# strategy 7 DPP instead of LDS round trips: NSA compressed pass 2 importance sums exchange lanes with v_mov_b32_dpp quad permutes instead of 32 ds_bpermute per tile
# speedup vs baseline: 1.0098x; 1.0025x over previous
; #define EXP2F(x) __builtin_amdgcn_exp2f(x)
; #define SB0 __builtin_amdgcn_sched_barrier(0)
; __device__ __forceinline__ void phase_nsa_attn(const Params& p, char* smem, volatile LAS unsigned* vb_) {
;     ...
;         for (int i = 0; i < ntile; ++i) {
;           const int n0 = i * 64;
;           const int nn = (i + 1 < ntile ? i + 1 : i) * 64;
;           f32x4 st[4];
;           qk64_lim(kA, qf, scale, nvalid - 1 - n0 - q * 4, st);
;           SB0;
;           k_load64(kA, Kb + (size_t)nn * 64, lane);
;           SB0;
; #pragma unroll
;           for (int kt = 0; kt < 4; ++kt)
; #pragma unroll
;             for (int r = 0; r < 4; ++r) st[kt][r] = EXP2F(st[kt][r] - m) * invl;
;           pv64(vA, st, o);
;           SB0;
;           v_load64(vA, Vb + (size_t)nn * 64, lane);
;           SB0;
;           float mainv[4], ev[4], eup[4];
; #pragma unroll
;           for (int kt = 0; kt < 4; ++kt) {
;             float acc = 0.f, last = 0.f;
; #pragma unroll
;             for (int r = 0; r < 4; ++r) {
;               float a = st[kt][r];
;               a += __shfl_xor(a, 1);
;               a += __shfl_xor(a, 2);
;               acc += a;
;               last = a;
;             }
.LBB0_97:
	s_waitcnt vmcnt(15)
	v_mfma_f32_16x16x32_bf16 v[68:71], v[68:71], v[4:7], 0
	s_waitcnt vmcnt(5)
	v_mov_b64_e32 v[102:103], v[82:83]
	s_mov_b32 s20, s11
	s_add_i32 s11, s11, 1
	v_mfma_f32_16x16x32_bf16 v[64:67], v[64:67], v[8:11], v[68:71]
	v_mov_b64_e32 v[100:101], v[80:81]
	v_mov_b32_e32 v0, s20
	v_mov_b32_e32 v80, s11
	v_mfma_f32_16x16x32_bf16 v[60:63], v[60:63], v[4:7], 0
	v_cmp_lt_i32_e32 vcc, s11, v159
	s_nop 2
	v_mul_f32_e32 v64, 0x3e38aa3b, v64
	s_waitcnt vmcnt(4)
	v_mov_b64_e32 v[94:95], v[86:87]
	v_cndmask_b32_e32 v0, v0, v80, vcc
	v_cmp_lt_i32_e32 vcc, -1, v179
	v_mfma_f32_16x16x32_bf16 v[52:55], v[52:55], v[8:11], v[60:63]
	v_mov_b64_e32 v[92:93], v[84:85]
	v_cndmask_b32_e32 v82, v203, v64, vcc
	v_mul_f32_e32 v64, 0x3e38aa3b, v65
	v_mfma_f32_16x16x32_bf16 v[44:47], v[44:47], v[4:7], 0
	v_cmp_lt_i32_e32 vcc, 0, v179
	s_nop 2
	v_mul_f32_e32 v52, 0x3e38aa3b, v52
	s_waitcnt vmcnt(1)
	v_mov_b64_e32 v[98:99], v[90:91]
	v_cndmask_b32_e32 v83, v203, v64, vcc
	v_mul_f32_e32 v64, 0x3e38aa3b, v66
	v_cmp_lt_i32_e32 vcc, 1, v179
	v_mfma_f32_16x16x32_bf16 v[40:43], v[40:43], v[8:11], v[44:47]
	v_mov_b64_e32 v[96:97], v[88:89]
	v_cndmask_b32_e32 v84, v203, v64, vcc
	v_mul_f32_e32 v64, 0x3e38aa3b, v67
	v_cmp_lt_i32_e32 vcc, 2, v179
	v_mfma_f32_16x16x32_bf16 v[36:39], v[36:39], v[4:7], 0
	s_nop 2
	v_mul_f32_e32 v40, 0x3e38aa3b, v40
	v_cndmask_b32_e32 v85, v203, v64, vcc
	v_cmp_lt_i32_e32 vcc, 15, v179
	v_mfma_f32_16x16x32_bf16 v[32:35], v[32:35], v[8:11], v[36:39]
	v_lshlrev_b32_e32 v0, 6, v0
	v_cndmask_b32_e32 v86, v203, v52, vcc
	v_mul_f32_e32 v52, 0x3e38aa3b, v53
	v_cmp_lt_i32_e32 vcc, 16, v179
	s_nop 1
	v_cndmask_b32_e32 v87, v203, v52, vcc
	v_mul_f32_e32 v52, 0x3e38aa3b, v54
	v_cmp_lt_i32_e32 vcc, 17, v179
	v_mul_f32_e32 v32, 0x3e38aa3b, v32
	s_nop 0
	v_cndmask_b32_e32 v88, v203, v52, vcc
	v_mul_f32_e32 v52, 0x3e38aa3b, v55
	v_cmp_lt_i32_e32 vcc, 18, v179
	s_nop 1
	v_cndmask_b32_e32 v89, v203, v52, vcc
	v_cmp_lt_i32_e32 vcc, 31, v179
	s_nop 1
	v_cndmask_b32_e32 v90, v203, v40, vcc
	v_mul_f32_e32 v40, 0x3e38aa3b, v41
	v_cmp_lt_i32_e32 vcc, 32, v179
	s_nop 1
	v_cndmask_b32_e32 v91, v203, v40, vcc
	v_mul_f32_e32 v40, 0x3e38aa3b, v42
	v_cmp_lt_i32_e32 vcc, 33, v179
	s_nop 1
	v_cndmask_b32_e32 v104, v203, v40, vcc
	v_mul_f32_e32 v40, 0x3e38aa3b, v43
	v_cmp_lt_i32_e32 vcc, 34, v179
	s_nop 1
	v_cndmask_b32_e32 v105, v203, v40, vcc
	v_cmp_lt_i32_e32 vcc, 47, v179
	s_nop 1
	v_cndmask_b32_e32 v106, v203, v32, vcc
	v_mul_f32_e32 v32, 0x3e38aa3b, v33
	v_cmp_lt_i32_e32 vcc, 48, v179
	s_nop 1
	v_cndmask_b32_e32 v107, v203, v32, vcc
	v_mul_f32_e32 v32, 0x3e38aa3b, v34
	v_cmp_lt_i32_e32 vcc, 49, v179
	s_nop 1
	v_cndmask_b32_e32 v108, v203, v32, vcc
	v_mul_f32_e32 v32, 0x3e38aa3b, v35
	v_cmp_lt_i32_e32 vcc, 50, v179
	s_nop 1
	v_cndmask_b32_e32 v109, v203, v32, vcc
	v_lshlrev_b64 v[80:81], 7, v[0:1]
	v_lshl_add_u64 v[32:33], v[122:123], 0, v[80:81]
	global_load_dwordx4 v[68:71], v[32:33], off
	global_load_dwordx4 v[64:67], v[32:33], off offset:1024
	global_load_dwordx4 v[60:63], v[32:33], off offset:2048
	global_load_dwordx4 v[52:55], v[32:33], off offset:3072
	v_add_co_u32_e32 v32, vcc, s33, v32
	s_nop 1
	v_addc_co_u32_e32 v33, vcc, 0, v33, vcc
	global_load_dwordx4 v[44:47], v[32:33], off
	global_load_dwordx4 v[40:43], v[32:33], off offset:1024
	global_load_dwordx4 v[36:39], v[32:33], off offset:2048
	s_nop 0
	global_load_dwordx4 v[32:35], v[32:33], off offset:3072
	v_sub_f32_e32 v0, v82, v180
	v_exp_f32_e32 v82, v0
	v_sub_f32_e32 v0, v83, v180
	v_exp_f32_e32 v83, v0
	v_sub_f32_e32 v0, v84, v180
	v_pk_mul_f32 v[184:185], v[2:3], v[82:83]
	v_exp_f32_e32 v82, v0
	v_sub_f32_e32 v0, v85, v180
	v_exp_f32_e32 v83, v0
	v_sub_f32_e32 v0, v86, v180
	v_exp_f32_e32 v84, v0
	v_sub_f32_e32 v0, v87, v180
	v_exp_f32_e32 v85, v0
	v_sub_f32_e32 v0, v88, v180
	v_exp_f32_e32 v86, v0
	v_sub_f32_e32 v0, v89, v180
	v_exp_f32_e32 v87, v0
	v_sub_f32_e32 v0, v90, v180
	v_exp_f32_e32 v88, v0
	v_sub_f32_e32 v0, v91, v180
	v_exp_f32_e32 v89, v0
	v_sub_f32_e32 v0, v104, v180
	v_pk_mul_f32 v[188:189], v[2:3], v[82:83]
	v_exp_f32_e32 v82, v0
	v_sub_f32_e32 v0, v105, v180
	v_exp_f32_e32 v83, v0
	v_sub_f32_e32 v0, v106, v180
	v_pk_mul_f32 v[190:191], v[2:3], v[84:85]
	v_exp_f32_e32 v84, v0
	v_sub_f32_e32 v0, v107, v180
	v_exp_f32_e32 v85, v0
	v_sub_f32_e32 v0, v108, v180
	v_pk_mul_f32 v[194:195], v[2:3], v[86:87]
	v_exp_f32_e32 v86, v0
	v_sub_f32_e32 v0, v109, v180
	v_exp_f32_e32 v87, v0
	v_cvt_pk_bf16_f32 v112, v184, v185
	v_cvt_pk_bf16_f32 v113, v188, v189
	v_cvt_pk_bf16_f32 v114, v190, v191
	v_cvt_pk_bf16_f32 v115, v194, v195
	v_pk_mul_f32 v[198:199], v[2:3], v[88:89]
	v_pk_mul_f32 v[204:205], v[2:3], v[82:83]
	v_mfma_f32_16x16x32_bf16 v[24:27], v[24:27], v[112:115], v[72:75]
	v_mul_f32_e64 v162, v2, v84
	v_mul_f32_e64 v163, v3, v85
	v_pk_mul_f32 v[160:161], v[2:3], v[86:87]
	v_cvt_pk_bf16_f32 v104, v198, v199
	v_mfma_f32_16x16x32_bf16 v[28:31], v[28:31], v[112:115], v[48:51]
	v_cvt_pk_bf16_f32 v105, v204, v205
	v_cvt_pk_bf16_f32 v106, v162, v163
	v_cvt_pk_bf16_f32 v107, v160, v161
	s_nop 1
	v_mfma_f32_16x16x32_bf16 v[72:75], v[12:15], v[104:107], v[24:27]
	v_mfma_f32_16x16x32_bf16 v[48:51], v[20:23], v[104:107], v[28:31]
	v_lshl_add_u64 v[20:21], v[132:133], 0, v[80:81]
	v_add_co_u32_e32 v108, vcc, s33, v20
	global_load_dwordx4 v[24:27], v[20:21], off
	global_load_dwordx4 v[12:15], v[20:21], off offset:1024
	global_load_dwordx4 v[80:83], v[20:21], off offset:2048
	global_load_dwordx4 v[84:87], v[20:21], off offset:3072
	v_addc_co_u32_e32 v109, vcc, 0, v21, vcc
	global_load_dwordx4 v[28:31], v[108:109], off
	global_load_dwordx4 v[20:23], v[108:109], off offset:1024
	global_load_dwordx4 v[88:91], v[108:109], off offset:2048
	s_nop 0
	global_load_dwordx4 v[108:111], v[108:109], off offset:3072
	v_mov_b32_dpp v186, v188 quad_perm:[1,0,3,2] row_mask:0xf bank_mask:0xf
	v_mov_b32_dpp v196, v195 quad_perm:[1,0,3,2] row_mask:0xf bank_mask:0xf
	v_mov_b32_dpp v206, v205 quad_perm:[1,0,3,2] row_mask:0xf bank_mask:0xf
	v_mov_b32_dpp v209, v161 quad_perm:[1,0,3,2] row_mask:0xf bank_mask:0xf
	v_mov_b32_dpp v0, v184 quad_perm:[1,0,3,2] row_mask:0xf bank_mask:0xf
	s_waitcnt lgkmcnt(4)
; __device__ __forceinline__ void phase_nsa_attn(const Params& p, char* smem, volatile LAS unsigned* vb_) {
;     ...
;           float mainv[4], ev[4], eup[4];
; #pragma unroll
;           for (int kt = 0; kt < 4; ++kt) {
;             float acc = 0.f, last = 0.f;
; #pragma unroll
;             for (int r = 0; r < 4; ++r) {
;               float a = st[kt][r];
;               a += __shfl_xor(a, 1);
;               a += __shfl_xor(a, 2);
;               acc += a;
;               last = a;
;             }
;             mainv[kt] = acc; ev[kt] = last;
;           }
; #pragma unroll
;           for (int kt = 0; kt < 4; ++kt) eup[kt] = __shfl(ev[kt], (lane + 48) & 63);
; #pragma unroll
;           for (int kt = 0; kt < 4; ++kt) {
;             const float pe = (q > 0) ? eup[kt] : (kt > 0 ? eup[kt > 0 ? kt - 1 : 0] : carry);
;             if (g == 0) impl[tq * 128 + (n0 >> 2) + kt * 4 + q] = mainv[kt] + pe;
;           }
;           carry = eup[3];
	v_add_f32_e32 v186, v188, v186
	v_mov_b32_dpp v188, v189 quad_perm:[1,0,3,2] row_mask:0xf bank_mask:0xf
	s_waitcnt lgkmcnt(4)
	v_add_f32_e32 v195, v195, v196
	s_nop 1
	v_mov_b32_dpp v196, v195 quad_perm:[2,3,0,1] row_mask:0xf bank_mask:0xf
	s_waitcnt lgkmcnt(4)
	v_add_f32_e32 v205, v205, v206
	s_nop 1
	v_mov_b32_dpp v206, v205 quad_perm:[2,3,0,1] row_mask:0xf bank_mask:0xf
	s_waitcnt lgkmcnt(2)
	v_add_f32_e32 v188, v189, v188
	s_nop 1
	v_mov_b32_dpp v189, v188 quad_perm:[2,3,0,1] row_mask:0xf bank_mask:0xf
	s_waitcnt lgkmcnt(2)
	v_add_f32_e32 v195, v195, v196
	v_mov_b32_dpp v196, v198 quad_perm:[1,0,3,2] row_mask:0xf bank_mask:0xf
	v_add_f32_e32 v161, v161, v209
	v_add_f32_e32 v0, v184, v0
	v_mov_b32_dpp v184, v185 quad_perm:[1,0,3,2] row_mask:0xf bank_mask:0xf
	s_waitcnt lgkmcnt(2)
	v_add_f32_e32 v188, v188, v189
	v_mov_b32_dpp v189, v190 quad_perm:[1,0,3,2] row_mask:0xf bank_mask:0xf
	v_mov_b32_dpp v192, v191 quad_perm:[1,0,3,2] row_mask:0xf bank_mask:0xf
	v_mov_b32_dpp v193, v194 quad_perm:[1,0,3,2] row_mask:0xf bank_mask:0xf
	s_waitcnt lgkmcnt(4)
	v_add_f32_e32 v196, v198, v196
	v_mov_b32_dpp v198, v199 quad_perm:[1,0,3,2] row_mask:0xf bank_mask:0xf
	v_mov_b32_dpp v200, v204 quad_perm:[1,0,3,2] row_mask:0xf bank_mask:0xf
	v_add_f32_e32 v205, v205, v206
	v_mov_b32_dpp v206, v162 quad_perm:[1,0,3,2] row_mask:0xf bank_mask:0xf
	v_mov_b32_dpp v207, v163 quad_perm:[1,0,3,2] row_mask:0xf bank_mask:0xf
	v_mov_b32_dpp v208, v160 quad_perm:[1,0,3,2] row_mask:0xf bank_mask:0xf
	v_mov_b32_dpp v209, v161 quad_perm:[2,3,0,1] row_mask:0xf bank_mask:0xf
	v_mfma_f32_16x16x32_bf16 v[56:59], v[100:103], v[112:115], v[56:59]
	s_waitcnt lgkmcnt(9)
	v_add_f32_e32 v184, v185, v184
	s_waitcnt lgkmcnt(8)
	v_add_f32_e32 v189, v190, v189
	s_waitcnt lgkmcnt(7)
	v_add_f32_e32 v191, v191, v192
	s_waitcnt lgkmcnt(6)
	v_add_f32_e32 v193, v194, v193
	s_waitcnt lgkmcnt(5)
	v_add_f32_e32 v198, v199, v198
	s_waitcnt lgkmcnt(4)
	v_add_f32_e32 v200, v204, v200
	s_waitcnt lgkmcnt(3)
	v_add_f32_e32 v162, v162, v206
	s_waitcnt lgkmcnt(2)
	v_add_f32_e32 v163, v163, v207
	s_waitcnt lgkmcnt(1)
	v_add_f32_e32 v160, v160, v208
	s_waitcnt lgkmcnt(0)
	v_add_f32_e32 v161, v161, v209
	v_mov_b32_dpp v183, v0 quad_perm:[2,3,0,1] row_mask:0xf bank_mask:0xf
	v_mov_b32_dpp v185, v184 quad_perm:[2,3,0,1] row_mask:0xf bank_mask:0xf
	v_mov_b32_dpp v187, v186 quad_perm:[2,3,0,1] row_mask:0xf bank_mask:0xf
	v_mov_b32_dpp v190, v189 quad_perm:[2,3,0,1] row_mask:0xf bank_mask:0xf
	v_mov_b32_dpp v192, v191 quad_perm:[2,3,0,1] row_mask:0xf bank_mask:0xf
	v_mov_b32_dpp v194, v193 quad_perm:[2,3,0,1] row_mask:0xf bank_mask:0xf
	v_mov_b32_dpp v197, v196 quad_perm:[2,3,0,1] row_mask:0xf bank_mask:0xf
	v_mov_b32_dpp v199, v198 quad_perm:[2,3,0,1] row_mask:0xf bank_mask:0xf
	v_mov_b32_dpp v204, v200 quad_perm:[2,3,0,1] row_mask:0xf bank_mask:0xf
	v_mov_b32_dpp v206, v162 quad_perm:[2,3,0,1] row_mask:0xf bank_mask:0xf
	v_mov_b32_dpp v207, v163 quad_perm:[2,3,0,1] row_mask:0xf bank_mask:0xf
	v_mov_b32_dpp v208, v160 quad_perm:[2,3,0,1] row_mask:0xf bank_mask:0xf
	v_mfma_f32_16x16x32_bf16 v[56:59], v[92:95], v[104:107], v[56:59]
	ds_bpermute_b32 v95, v172, v188
	ds_bpermute_b32 v94, v172, v195
	ds_bpermute_b32 v93, v172, v205
	ds_bpermute_b32 v92, v172, v161
	v_mfma_f32_16x16x32_bf16 v[76:79], v[96:99], v[112:115], v[76:79]
	s_and_saveexec_b64 s[20:21], s[44:45]
	s_cbranch_execz .LBB0_96
	s_waitcnt lgkmcnt(6)
	v_add_f32_e32 v96, v162, v206
	v_add_f32_e32 v99, v189, v190
	v_add_f32_e32 v96, 0, v96
	s_waitcnt lgkmcnt(5)
	v_add_f32_e32 v97, v163, v207
	v_add_f32_e32 v99, 0, v99
	v_add_f32_e32 v100, v191, v192
	v_add_f32_e32 v96, v96, v97
	s_waitcnt lgkmcnt(4)
	v_add_f32_e32 v97, v160, v208
	v_add_f32_e32 v99, v99, v100
	v_add_f32_e32 v100, v193, v194
	v_add_f32_e32 v0, v0, v183
	v_add_f32_e32 v96, v96, v97
	v_add_f32_e32 v97, v196, v197
	v_add_f32_e32 v99, v99, v100
	v_add_f32_e32 v0, 0, v0
	v_add_f32_e32 v100, v184, v185
	v_add_f32_e32 v97, 0, v97
	v_add_f32_e32 v98, v198, v199
	v_add_f32_e32 v0, v0, v100
	v_add_f32_e32 v100, v186, v187
	v_add_f32_e32 v97, v97, v98
	v_add_f32_e32 v98, v200, v204
	v_add_f32_e32 v0, v0, v100
	v_add_f32_e32 v97, v97, v98
	s_waitcnt lgkmcnt(3)
	v_cndmask_b32_e64 v98, v95, v181, s[42:43]
	v_add_f32_e32 v99, v99, v195
	v_add_f32_e32 v0, v0, v188
	s_waitcnt lgkmcnt(2)
	v_cndmask_b32_e64 v95, v94, v95, s[42:43]
	v_add_f32_e32 v0, v0, v98
	v_add_f32_e32 v95, v99, v95
	v_add_f32_e32 v96, v96, v161
	v_add_f32_e32 v97, v97, v205
	ds_write2_b32 v182, v0, v95 offset1:4
	s_waitcnt lgkmcnt(2)
	v_cndmask_b32_e64 v0, v93, v94, s[42:43]
	s_waitcnt lgkmcnt(1)
	v_cndmask_b32_e64 v93, v92, v93, s[42:43]
	v_add_f32_e32 v0, v97, v0
	v_add_f32_e32 v93, v96, v93
	ds_write2_b32 v182, v0, v93 offset0:8 offset1:12
	s_branch .LBB0_96
